# phase 0 weight transposes: contiguous tile chunk per workgroup and L2 touch of the tile two ahead
# baseline (speedup 1.0000x reference)
.LBB0_537:
	v_readlane_b32 s2, v254, 18
	v_readlane_b32 s3, v254, 19
	v_mov_b32_e32 v0, v204
	s_andn2_b64 vcc, exec, s[2:3]
	s_cbranch_vccnz .LBB0_617
	v_readlane_b32 s2, v254, 49
	v_readlane_b32 s3, v254, 50
	s_mov_b32 vcc_lo, 0
	s_mov_b32 vcc_hi, 0
.Lwt_chunk:
	s_add_i32 vcc_lo, vcc_lo, s96
	s_add_i32 vcc_hi, vcc_hi, 1
	s_cmpk_lt_i32 vcc_lo, 0x2270
	s_cbranch_scc1 .Lwt_chunk
	s_mul_i32 s0, s2, vcc_hi
	s_add_i32 s1, s0, vcc_hi
	s_add_i32 s1, s1, -1
	s_min_i32 s1, s1, 0x226f
	s_cmp_gt_i32 s0, s1
	s_cbranch_scc1 .LBB0_617
	s_branch .LBB0_540
.LBB0_539:
	s_or_b64 exec, exec, s[4:5]
	s_add_i32 s0, s0, 1
	s_cmp_gt_i32 s0, s1
	s_barrier
	s_cbranch_scc1 .LBB0_617

.LBB0_613:
	s_mul_i32 s12, s12, s11
	s_sub_i32 s8, s17, s12
	s_sext_i32_i16 s8, s8
	v_lshlrev_b32_e32 v1, 3, v1
	s_lshl_b32 s8, s8, 6
	v_and_b32_e32 v1, 56, v1
	v_or_b32_e32 v5, s8, v1
	v_cmp_gt_i32_e32 vcc, s16, v5
	s_and_saveexec_b64 s[12:13], vcc
	s_cbranch_execz .LBB0_615
	v_mad_i64_i32 v[4:5], s[14:15], v4, s16, 0
	v_lshl_add_u64 v[4:5], v[4:5], 2, s[4:5]
	s_ashr_i32 s9, s8, 31
	v_lshl_add_u64 v[4:5], s[8:9], 2, v[4:5]
	v_lshlrev_b32_e32 v188, 2, v1
	v_lshl_add_u64 v[8:9], v[4:5], 0, v[188:189]
	s_add_i32 s14, s8, 0x80
	s_lshl_b32 s15, s11, 6
	s_cmp_ge_i32 s14, s15
	s_cselect_b32 vcc_hi, s15, 0
	s_cselect_b32 s15, 64, 0
	s_sub_i32 s14, s14, vcc_hi
	s_add_i32 vcc_lo, s10, s15
	s_mul_i32 s15, s15, s16
	s_sub_i32 s14, s14, s8
	s_add_i32 s14, s14, s15
	s_lshl_b32 s14, s14, 2
	s_cmp_lt_i32 vcc_lo, s3
	s_cselect_b32 s14, s14, 0
	s_ashr_i32 s15, s14, 31
	v_lshl_add_u64 v[246:247], s[14:15], 0, v[8:9]
	global_load_dwordx4 v[4:7], v[8:9], off
	s_nop 0
	global_load_dwordx4 v[8:11], v[8:9], off offset:16
	global_load_dwordx4 v[248:251], v[246:247], off
	global_load_dwordx4 v[248:251], v[246:247], off offset:16
	s_movk_i32 s4, 0x104
	v_mul_lo_u32 v12, v3, s4
	v_add3_u32 v12, 0, v12, v188
	s_waitcnt vmcnt(2)
	v_pk_mul_f32 v[4:5], v[2:3], v[4:5] op_sel_hi:[0,1]
	v_pk_mul_f32 v[6:7], v[2:3], v[6:7] op_sel_hi:[0,1]
	v_pk_mul_f32 v[8:9], v[2:3], v[8:9] op_sel_hi:[0,1]
	v_pk_mul_f32 v[10:11], v[2:3], v[10:11] op_sel_hi:[0,1]
	ds_write2_b32 v12, v4, v5 offset1:1
	ds_write2_b32 v12, v6, v7 offset0:2 offset1:3
	ds_write2_b32 v12, v8, v9 offset0:4 offset1:5
	ds_write2_b32 v12, v10, v11 offset0:6 offset1:7
.LBB0_615:
	s_or_b64 exec, exec, s[12:13]
	s_waitcnt vmcnt(2)
	v_add_u32_e32 v2, s8, v3
	v_cmp_gt_i32_e32 vcc, s16, v2
	s_waitcnt lgkmcnt(0)
	s_barrier
	s_and_saveexec_b64 s[4:5], vcc
	s_cbranch_execz .LBB0_539
	s_mul_hi_i32 s8, s2, 0x2260000
	s_mul_i32 s2, s2, 0x2260000
	v_mul_u32_u24_e32 v4, 0x104, v1
	v_lshlrev_b32_e32 v3, 2, v3
	s_add_u32 s2, s48, s2
	v_add3_u32 v3, 0, v4, v3
	s_addc_u32 s9, s49, s8
	s_lshl_b32 s6, s6, 1
	ds_read2_b32 v[4:5], v3 offset1:65
	ds_read2_b32 v[6:7], v3 offset0:130 offset1:195
	v_add_u32_e32 v3, 0x400, v3
	s_add_u32 s8, s2, s6
	ds_read2_b32 v[8:9], v3 offset0:4 offset1:69
	ds_read2_b32 v[10:11], v3 offset0:134 offset1:199
	s_addc_u32 s9, s9, 0
	s_cmp_eq_u32 s7, 0
	s_cselect_b64 vcc, -1, 0
	v_lshlrev_b32_e32 v3, 1, v2
	s_cmp_eq_u32 s7, 2
	s_waitcnt lgkmcnt(3)
	v_cvt_pk_bf16_f32 v4, v4, v5
	s_waitcnt lgkmcnt(2)
	v_cvt_pk_bf16_f32 v5, v6, v7
	s_waitcnt lgkmcnt(1)
	v_cvt_pk_bf16_f32 v6, v8, v9
	v_and_b32_e32 v3, 0xffffff00, v3
	v_and_b32_e32 v8, 0x7f, v2
	s_cselect_b32 s2, 0x80, 0
	v_or3_b32 v3, v8, s2, v3
	v_cndmask_b32_e32 v2, v3, v2, vcc
	v_mad_i64_i32 v[2:3], s[2:3], v2, s3, 0
	v_lshl_add_u64 v[2:3], v[2:3], 1, s[8:9]
	s_ashr_i32 s11, s10, 31
	v_lshl_add_u64 v[2:3], s[10:11], 1, v[2:3]
	v_lshlrev_b32_e32 v188, 1, v1
	s_waitcnt lgkmcnt(0)
	v_cvt_pk_bf16_f32 v7, v10, v11
	v_lshl_add_u64 v[2:3], v[2:3], 0, v[188:189]
	global_store_dwordx4 v[2:3], v[4:7], off
	s_branch .LBB0_539
.LBB0_617:
	s_waitcnt vmcnt(0)
	s_mov_b32 s1, 0
	v_readlane_b32 s2, v254, 20
	v_readlane_b32 s3, v254, 21
	s_mov_b32 s6, 0x6dc9c883
	s_andn2_b64 vcc, exec, s[2:3]
	v_add_u32_e32 v2, s76, v0
	s_mov_b32 s7, 0x3fc45f30
	s_cbranch_vccnz .LBB0_620
	v_and_b32_e32 v3, 15, v0
	v_cvt_f32_ubyte0_e32 v1, v3
	v_mul_f32_e32 v1, 0xbd800000, v1
	v_cmp_eq_f32_e32 vcc, 0, v1
	s_mov_b32 s0, 0x3f2aaaab
	s_movk_i32 s8, 0x204
	v_cndmask_b32_e64 v14, v212, 1.0, vcc
	v_frexp_mant_f32_e32 v4, v14
	v_cmp_gt_f32_e64 s[4:5], s0, v4
	s_mov_b32 s0, 0x3f317218
	s_mov_b32 s2, 0x42b17218
	v_cndmask_b32_e64 v5, 1.0, 2.0, s[4:5]
	v_mul_f32_e32 v4, v4, v5
	v_add_f32_e32 v7, 1.0, v4
	v_rcp_f32_e32 v12, v7
	v_add_f32_e32 v5, -1.0, v4
	v_add_f32_e32 v6, -1.0, v7
	v_sub_f32_e32 v4, v4, v6
	v_mul_f32_e32 v13, v5, v12
	v_mul_f32_e32 v6, v7, v13
	v_fma_f32 v8, v13, v7, -v6
	v_fmac_f32_e32 v8, v13, v4
	v_add_f32_e32 v4, v6, v8
	v_sub_f32_e32 v7, v5, v4
	v_pk_add_f32 v[10:11], v[4:5], v[6:7] neg_lo:[0,1] neg_hi:[0,1]
	v_mov_b32_e32 v9, v4
	v_pk_add_f32 v[4:5], v[10:11], v[8:9] neg_lo:[0,1] neg_hi:[0,1]
	v_mov_b32_e32 v8, 0x3e91f4c4
	v_add_f32_e32 v4, v4, v5
	v_add_f32_e32 v4, v7, v4
	v_mul_f32_e32 v5, v12, v4
	v_add_f32_e32 v4, v13, v5
	v_sub_f32_e32 v6, v4, v13
	v_sub_f32_e32 v15, v5, v6
	v_mul_f32_e32 v5, v4, v4
	v_fma_f32 v7, v4, v4, -v5
	v_add_f32_e32 v6, v15, v15
	v_fmac_f32_e32 v7, v4, v6
	v_add_f32_e32 v6, v5, v7
	v_fmamk_f32 v8, v6, 0x3e76c4e1, v8
	v_fmaak_f32 v8, v6, v8, 0x3ecccdef
	v_sub_f32_e32 v5, v6, v5
	v_sub_f32_e32 v16, v7, v5
	v_mul_f32_e32 v5, v6, v8
	v_fma_f32 v7, v6, v8, -v5
	v_fmac_f32_e32 v7, v16, v8
	v_add_f32_e32 v8, v5, v7
	v_add_f32_e32 v9, 0x3f2aaaaa, v8
	v_sub_f32_e32 v5, v8, v5
	v_sub_f32_e32 v5, v7, v5
	v_add_f32_e32 v7, 0xbf2aaaaa, v9
	v_add_f32_e32 v5, 0x31739010, v5
	v_sub_f32_e32 v7, v8, v7
	v_pk_mul_f32 v[10:11], v[4:5], v[6:7]
	v_pk_add_f32 v[12:13], v[4:5], v[6:7]
	v_fma_f32 v8, v6, v4, -v10
	v_fmac_f32_e32 v8, v6, v15
	v_mov_b32_e32 v11, v13
	v_fmac_f32_e32 v8, v16, v4
	v_pk_add_f32 v[6:7], v[10:11], v[8:9]
	v_ldexp_f32 v16, v15, 1
	v_sub_f32_e32 v5, v6, v10
	v_sub_f32_e32 v5, v8, v5
	v_sub_f32_e32 v8, v9, v7
	v_add_f32_e32 v12, v13, v8
	v_pk_mul_f32 v[8:9], v[6:7], v[6:7] op_sel:[0,1] op_sel_hi:[1,0]
	v_cvt_f64_f32_e32 v[10:11], v14
	v_frexp_exp_i32_f64_e32 v9, v[10:11]
	v_subbrev_co_u32_e64 v9, s[4:5], 0, v9, s[4:5]
	v_cvt_f32_i32_e32 v9, v9
	v_fma_f32 v10, v6, v7, -v8
	v_fmac_f32_e32 v10, v6, v12
	v_fmac_f32_e32 v10, v5, v7
	v_mul_f32_e32 v6, 0x3f317218, v9
	v_fma_f32 v12, v9, s0, -v6
	v_fmac_f32_e32 v12, 0xb102e308, v9
	v_ldexp_f32 v13, v4, 1
	v_add_f32_e32 v7, v8, v10
	v_pk_add_f32 v[4:5], v[6:7], v[12:13]
	v_mov_b32_e32 v14, v7
	v_mov_b32_e32 v15, v5
	v_mov_b32_e32 v9, v13
	v_pk_add_f32 v[8:9], v[14:15], v[8:9] neg_lo:[0,1] neg_hi:[0,1]
	v_mov_b32_e32 v11, v7
	v_pk_add_f32 v[8:9], v[10:11], v[8:9] neg_lo:[0,1] neg_hi:[0,1]
	v_mov_b32_e32 v13, v4
	v_add_f32_e32 v7, v16, v8
	v_add_f32_e32 v7, v7, v9
	v_pk_add_f32 v[8:9], v[4:5], v[6:7] neg_lo:[0,1] neg_hi:[0,1]
	v_pk_add_f32 v[10:11], v[4:5], v[6:7]
	v_mov_b32_e32 v6, v7
	v_mov_b32_e32 v9, v11
	v_pk_add_f32 v[14:15], v[12:13], v[8:9] neg_lo:[0,1] neg_hi:[0,1]
	v_pk_add_f32 v[8:9], v[12:13], v[8:9]
	v_mov_b32_e32 v7, v4
	v_pk_add_f32 v[12:13], v[8:9], v[4:5] op_sel:[1,0] op_sel_hi:[0,1] neg_lo:[0,1] neg_hi:[0,1]
	v_pk_add_f32 v[16:17], v[10:11], v[12:13] op_sel_hi:[1,0] neg_lo:[0,1] neg_hi:[0,1]
	v_mov_b32_e32 v10, v11
	v_mov_b32_e32 v11, v9
	v_pk_mov_b32 v[12:13], v[4:5], v[12:13] op_sel:[1,0]
	v_mov_b32_e32 v16, v14
	v_pk_add_f32 v[10:11], v[10:11], v[12:13] neg_lo:[0,1] neg_hi:[0,1]
	v_mov_b32_e32 v15, v9
	v_pk_add_f32 v[4:5], v[6:7], v[10:11] neg_lo:[0,1] neg_hi:[0,1]
	s_mov_b32 s0, 0x3fb8aa3b
	v_pk_add_f32 v[6:7], v[16:17], v[4:5]
	v_lshlrev_b32_e32 v188, 2, v3
	v_pk_add_f32 v[10:11], v[6:7], v[6:7] op_sel:[0,1] op_sel_hi:[1,0]
	v_add_u32_e32 v3, s76, v0
	v_pk_add_f32 v[8:9], v[8:9], v[10:11] op_sel:[1,0] op_sel_hi:[0,1]
	v_mov_b32_e32 v7, v8
	v_pk_add_f32 v[12:13], v[6:7], v[14:15] neg_lo:[0,1] neg_hi:[0,1]
	v_mov_b32_e32 v5, v10
	v_sub_f32_e32 v6, v6, v12
	v_pk_add_f32 v[4:5], v[4:5], v[12:13] neg_lo:[0,1] neg_hi:[0,1]
	v_sub_f32_e32 v6, v14, v6
	v_add_f32_e32 v4, v4, v6
	v_add_f32_e32 v4, v4, v5
	v_add_f32_e32 v5, v8, v4
	v_sub_f32_e32 v6, v5, v8
	v_sub_f32_e32 v4, v4, v6
	v_mul_f32_e32 v6, v1, v5
	v_fma_f32 v5, v1, v5, -v6
	v_fmac_f32_e32 v5, v1, v4
	v_add_f32_e32 v4, v6, v5
	v_cmp_class_f32_e64 s[4:5], v6, s8
	v_sub_f32_e32 v7, v4, v6
	v_sub_f32_e32 v5, v5, v7
	v_cndmask_b32_e64 v4, v4, v6, s[4:5]
	v_cmp_eq_f32_e64 s[4:5], s2, v4
	s_nop 1
	v_cndmask_b32_e64 v6, 0, v213, s[4:5]
	v_sub_f32_e32 v7, v4, v6
	v_mul_f32_e32 v8, 0x3fb8aa3b, v7
	v_fma_f32 v9, v7, s0, -v8
	v_rndne_f32_e32 v10, v8
	v_fmac_f32_e32 v9, 0x32a5705f, v7
	v_sub_f32_e32 v8, v8, v10
	v_add_f32_e32 v8, v8, v9
	v_exp_f32_e32 v8, v8
	v_cvt_i32_f32_e32 v9, v10
	s_mov_b32 s0, 0x7f800000
	v_cmp_neq_f32_e64 s[4:5], |v4|, s0
	s_mov_b32 s0, 0xc2ce8ed0
	s_nop 0
	v_cndmask_b32_e64 v4, 0, v5, s[4:5]
	v_ldexp_f32 v5, v8, v9
	v_cmp_ngt_f32_e64 s[4:5], s0, v7
	v_add_f32_e32 v4, v6, v4
	s_nop 0
	v_cndmask_b32_e64 v5, 0, v5, s[4:5]
	v_cmp_nlt_f32_e64 s[4:5], s2, v7
	v_cmp_neq_f32_e64 s[2:3], v1, |v1|
	s_nop 0
	v_cndmask_b32_e64 v5, v214, v5, s[4:5]
	v_fma_f32 v4, v5, v4, v5
	v_cmp_class_f32_e64 s[4:5], v5, s8
	s_nop 1
	v_cndmask_b32_e64 v4, v4, v5, s[4:5]
	v_cndmask_b32_e64 v5, v214, 0, s[2:3]
	v_cndmask_b32_e64 v5, v5, 1.0, vcc
	v_cmp_class_f32_e64 s[2:3], v1, s8
	s_nop 1
	v_cndmask_b32_e64 v1, |v4|, v5, s[2:3]
	v_readlane_b32 s2, v252, 50
	v_readlane_b32 s3, v252, 51
	s_nop 1
	v_lshl_add_u64 v[4:5], s[2:3], 0, v[188:189]
	v_readlane_b32 s2, v254, 49
	s_mov_b32 s0, s2
	v_readlane_b32 s3, v254, 50
